# attention inner loop: row sums accumulated with packed f32 adds into a free register pair; first tile max-subtractions packed
# baseline (speedup 1.0000x reference)
.LBB0_329:
	v_add_u32_e32 v112, s20, v214
	ds_read_b64_tr_b16 v[166:167], v112 offset:24576
	ds_read_b64_tr_b16 v[168:169], v112 offset:25088
	v_pk_add_f32 v[186:187], v[80:81], v[82:83]
	s_setprio 1
	s_waitcnt lgkmcnt(4)
	v_mfma_f32_32x32x16_bf16 v[32:47], v[158:161], v[126:129], v[32:47]
	s_setprio 0
	v_pk_add_f32 v[186:187], v[186:187], v[84:85]
	v_pk_add_f32 v[186:187], v[186:187], v[86:87]
	v_cvt_pk_bf16_f32 v142, v80, v81
	v_cvt_pk_bf16_f32 v143, v82, v83
	ds_read_b64_tr_b16 v[158:159], v112 offset:28672
	ds_read_b64_tr_b16 v[160:161], v112 offset:29184
	s_setprio 1
	s_waitcnt lgkmcnt(4)
	v_mfma_f32_32x32x16_bf16 v[48:63], v[154:157], v[126:129], v[48:63]
	s_setprio 0
	v_pk_add_f32 v[186:187], v[186:187], v[88:89]
	v_pk_add_f32 v[186:187], v[186:187], v[90:91]
	v_cvt_pk_bf16_f32 v144, v84, v85
	v_cvt_pk_bf16_f32 v145, v86, v87
	ds_read_b64_tr_b16 v[154:155], v112 offset:25600
	ds_read_b64_tr_b16 v[156:157], v112 offset:26112
	s_setprio 1
	v_mfma_f32_32x32x16_bf16 v[32:47], v[150:153], v[122:125], v[32:47]
	s_setprio 0
	v_pk_add_f32 v[186:187], v[186:187], v[92:93]
	v_pk_add_f32 v[186:187], v[186:187], v[94:95]
	v_cvt_pk_bf16_f32 v138, v88, v89
	v_cvt_pk_bf16_f32 v139, v90, v91
	ds_read_b64_tr_b16 v[162:163], v112 offset:29696
	ds_read_b64_tr_b16 v[164:165], v112 offset:30208
	s_setprio 1
	v_mfma_f32_32x32x16_bf16 v[48:63], v[146:149], v[122:125], v[48:63]
	s_setprio 0
	v_pk_add_f32 v[186:187], v[186:187], v[64:65]
	v_pk_add_f32 v[186:187], v[186:187], v[66:67]
	v_cvt_pk_bf16_f32 v140, v92, v93
	v_cvt_pk_bf16_f32 v141, v94, v95
	ds_read_b64_tr_b16 v[92:93], v112 offset:26624
	ds_read_b64_tr_b16 v[94:95], v112 offset:27136
	s_setprio 1
	v_mfma_f32_32x32x16_bf16 v[32:47], v[108:111], v[118:121], v[32:47]
	s_setprio 0
	v_pk_add_f32 v[186:187], v[186:187], v[68:69]
	v_pk_add_f32 v[186:187], v[186:187], v[70:71]
	v_cvt_pk_bf16_f32 v134, v64, v65
	v_cvt_pk_bf16_f32 v135, v66, v67
	ds_read_b64_tr_b16 v[88:89], v112 offset:30720
	ds_read_b64_tr_b16 v[90:91], v112 offset:31232
	s_setprio 1
	v_mfma_f32_32x32x16_bf16 v[48:63], v[100:103], v[118:121], v[48:63]
	s_setprio 0
	v_pk_add_f32 v[186:187], v[186:187], v[72:73]
	v_pk_add_f32 v[186:187], v[186:187], v[74:75]
	v_cvt_pk_bf16_f32 v136, v68, v69
	v_cvt_pk_bf16_f32 v137, v70, v71
	ds_read_b64_tr_b16 v[84:85], v112 offset:27648
	ds_read_b64_tr_b16 v[86:87], v112 offset:28160
	s_setprio 1
	v_mfma_f32_32x32x16_bf16 v[32:47], v[104:107], v[114:117], v[32:47]
	s_setprio 0
	v_pk_add_f32 v[186:187], v[186:187], v[76:77]
	v_pk_add_f32 v[186:187], v[186:187], v[78:79]
	v_cvt_pk_bf16_f32 v130, v72, v73
	v_cvt_pk_bf16_f32 v131, v74, v75
	ds_read_b64_tr_b16 v[80:81], v112 offset:31744
	ds_read_b64_tr_b16 v[82:83], v112 offset:32256
	s_setprio 1
	v_mfma_f32_32x32x16_bf16 v[48:63], v[96:99], v[114:117], v[48:63]
	s_setprio 0
	v_add_f32_e32 v64, v186, v187
	v_cvt_pk_bf16_f32 v132, v76, v77
	v_cvt_pk_bf16_f32 v133, v78, v79
	v_max_f32_e32 v65, v33, v33
	v_max_f32_e32 v66, v32, v32
	v_max_f32_e32 v65, v66, v65
	s_nop 2
	v_max3_f32 v66, v34, v35, v49
	v_max3_f32 v65, v65, v48, v50
	v_max3_f32 v65, v65, v51, v36
	v_max3_f32 v66, v66, v38, v39
	v_max3_f32 v65, v65, v37, v52
	v_max3_f32 v66, v66, v54, v55
	v_max3_f32 v65, v65, v53, v40
	v_max3_f32 v66, v66, v42, v43
	v_max3_f32 v65, v65, v41, v56
	v_max3_f32 v66, v66, v58, v59
	v_max3_f32 v65, v65, v57, v44
	v_max3_f32 v66, v66, v46, v47
	v_max3_f32 v65, v65, v45, v60
	v_max3_f32 v66, v66, v62, v63
	v_add_f32_e32 v170, v203, v64
	v_max3_f32 v64, v65, v61, v66
	v_mov_b32_e32 v65, v64
	s_nop 1
	v_permlane32_swap_b32_e32 v64, v65
	s_add_u32 s20, s18, 0xffff0000
	v_max_f32_e32 v65, v65, v65
	v_max_f32_e32 v64, v64, v64
	s_addc_u32 s21, s19, -1
	s_add_i32 s22, s48, s40
	v_max_f32_e32 v64, v64, v65
	s_mov_b32 s23, m0
	s_mov_b32 m0, s22
	s_nop 0
	global_load_lds_dwordx4 v211, s[20:21]
	s_mov_b32 m0, s23
	s_add_u32 s20, s0, 0xffff0000
	v_sub_f32_e32 v64, v64, v206
	s_addc_u32 s21, s1, -1
	s_add_i32 s22, s45, s41
	s_mov_b32 s23, m0
	s_mov_b32 m0, s22
	s_nop 0
	global_load_lds_dwordx4 v212, s[20:21]
	s_mov_b32 m0, s23
	v_cmp_lt_f32_e32 vcc, s35, v64
	s_cmp_lg_u64 vcc, 0
	s_cselect_b64 s[20:21], -1, 0
	s_cbranch_vccz .LBB0_333
	v_max_f32_e32 v64, v64, v64
	v_max_f32_e32 v65, 0, v64
	v_exp_f32_e64 v64, -v65
	s_and_saveexec_b64 s[22:23], s[4:5]
	ds_write_b32 v199, v64 offset:49152
	s_or_b64 exec, exec, s[22:23]
	v_add_f32_e32 v206, v206, v65
	v_mul_f32_e32 v170, v170, v64
.LBB0_333:
	v_pk_add_f32 v[32:33], v[32:33], v[206:207] op_sel_hi:[1,0] neg_lo:[0,1] neg_hi:[0,1]
	v_pk_add_f32 v[48:49], v[48:49], v[206:207] op_sel_hi:[1,0] neg_lo:[0,1] neg_hi:[0,1]
	v_pk_add_f32 v[34:35], v[34:35], v[206:207] op_sel_hi:[1,0] neg_lo:[0,1] neg_hi:[0,1]
	v_pk_add_f32 v[50:51], v[50:51], v[206:207] op_sel_hi:[1,0] neg_lo:[0,1] neg_hi:[0,1]
	v_pk_add_f32 v[64:65], v[36:37], v[206:207] op_sel_hi:[1,0] neg_lo:[0,1] neg_hi:[0,1]
	v_pk_add_f32 v[36:37], v[52:53], v[206:207] op_sel_hi:[1,0] neg_lo:[0,1] neg_hi:[0,1]
	v_pk_add_f32 v[66:67], v[38:39], v[206:207] op_sel_hi:[1,0] neg_lo:[0,1] neg_hi:[0,1]
	v_pk_add_f32 v[38:39], v[54:55], v[206:207] op_sel_hi:[1,0] neg_lo:[0,1] neg_hi:[0,1]
	v_pk_add_f32 v[68:69], v[40:41], v[206:207] op_sel_hi:[1,0] neg_lo:[0,1] neg_hi:[0,1]
	v_pk_add_f32 v[40:41], v[56:57], v[206:207] op_sel_hi:[1,0] neg_lo:[0,1] neg_hi:[0,1]
	v_pk_add_f32 v[70:71], v[42:43], v[206:207] op_sel_hi:[1,0] neg_lo:[0,1] neg_hi:[0,1]
	v_pk_add_f32 v[42:43], v[58:59], v[206:207] op_sel_hi:[1,0] neg_lo:[0,1] neg_hi:[0,1]
	v_pk_add_f32 v[72:73], v[44:45], v[206:207] op_sel_hi:[1,0] neg_lo:[0,1] neg_hi:[0,1]
	v_pk_add_f32 v[44:45], v[60:61], v[206:207] op_sel_hi:[1,0] neg_lo:[0,1] neg_hi:[0,1]
	v_pk_add_f32 v[74:75], v[46:47], v[206:207] op_sel_hi:[1,0] neg_lo:[0,1] neg_hi:[0,1]
	v_pk_add_f32 v[46:47], v[62:63], v[206:207] op_sel_hi:[1,0] neg_lo:[0,1] neg_hi:[0,1]
	s_setprio 1
	s_waitcnt lgkmcnt(14)
	v_mfma_f32_32x32x16_bf16 v[16:31], v[142:145], v[166:169], v[16:31]
	s_setprio 0
	v_exp_f32_e32 v60, v32
	v_exp_f32_e32 v61, v33
	v_exp_f32_e32 v62, v34
	v_exp_f32_e32 v63, v35
	s_setprio 1
	s_waitcnt lgkmcnt(12)
	v_mfma_f32_32x32x16_bf16 v[0:15], v[142:145], v[158:161], v[0:15]
	s_setprio 0
	v_exp_f32_e32 v64, v64
	v_exp_f32_e32 v65, v65
	v_exp_f32_e32 v66, v66
	v_exp_f32_e32 v67, v67
	v_add_u32_e32 v96, s45, v213
	ds_read_b128 v[158:161], v96
	ds_read_b128 v[150:153], v96 offset:512
	s_setprio 1
	s_waitcnt lgkmcnt(12)
	v_mfma_f32_32x32x16_bf16 v[16:31], v[138:141], v[154:157], v[16:31]
	s_setprio 0
	v_exp_f32_e32 v68, v68
	v_exp_f32_e32 v69, v69
	v_exp_f32_e32 v70, v70
	v_exp_f32_e32 v71, v71
	ds_read_b128 v[154:157], v96 offset:2048
	ds_read_b128 v[76:79], v96 offset:2560
	s_setprio 1
	s_waitcnt lgkmcnt(12)
	v_mfma_f32_32x32x16_bf16 v[0:15], v[138:141], v[162:165], v[0:15]
	s_setprio 0
	v_exp_f32_e32 v72, v72
	v_exp_f32_e32 v73, v73
	v_exp_f32_e32 v74, v74
	v_exp_f32_e32 v75, v75
	ds_read_b128 v[146:149], v96 offset:4096
	ds_read_b128 v[52:55], v96 offset:4608
	s_setprio 1
	s_waitcnt lgkmcnt(12)
	v_mfma_f32_32x32x16_bf16 v[16:31], v[134:137], v[92:95], v[16:31]
	s_setprio 0
	v_exp_f32_e32 v32, v48
	v_exp_f32_e32 v33, v49
	v_exp_f32_e32 v34, v50
	v_exp_f32_e32 v35, v51
	ds_read_b128 v[56:59], v96 offset:6144
	ds_read_b128 v[48:51], v96 offset:6656
	s_setprio 1
	s_waitcnt lgkmcnt(12)
	v_mfma_f32_32x32x16_bf16 v[0:15], v[134:137], v[88:91], v[0:15]
	s_setprio 0
	v_exp_f32_e32 v36, v36
	v_exp_f32_e32 v37, v37
	v_exp_f32_e32 v38, v38
	v_exp_f32_e32 v39, v39
	s_setprio 1
	s_waitcnt lgkmcnt(10)
	v_mfma_f32_32x32x16_bf16 v[16:31], v[130:133], v[84:87], v[16:31]
	s_setprio 0
	v_exp_f32_e32 v40, v40
	v_exp_f32_e32 v41, v41
	v_exp_f32_e32 v42, v42
	v_exp_f32_e32 v43, v43
	s_setprio 1
	s_waitcnt lgkmcnt(8)
	v_mfma_f32_32x32x16_bf16 v[0:15], v[130:133], v[80:83], v[0:15]
	s_setprio 0
	v_exp_f32_e32 v44, v44
	v_exp_f32_e32 v45, v45
	v_exp_f32_e32 v46, v46
	v_exp_f32_e32 v47, v47
	v_mov_b32_e32 v80, v210
	s_andn2_b64 vcc, exec, s[20:21]
	v_lshl_add_u32 v80, v80, 4, s46
	ds_read_b128 v[98:101], v80
	ds_read_b128 v[102:105], v80 offset:32
	ds_read_b128 v[82:85], v80 offset:128
	ds_read_b128 v[86:89], v80 offset:160
	ds_read_b128 v[106:109], v80 offset:64
	ds_read_b128 v[110:113], v80 offset:96
	ds_read_b128 v[90:93], v80 offset:192
	ds_read_b128 v[94:97], v80 offset:224
	s_waitcnt vmcnt(2) lgkmcnt(0)
	s_barrier
	s_cbranch_vccnz .LBB0_335
	s_waitcnt lgkmcnt(0)
	v_add_u32_e32 v80, s39, v216
	ds_read_b128 v[162:165], v80 offset:49248
	ds_read_b128 v[166:169], v80 offset:49216
	ds_read_b128 v[172:175], v80 offset:49184
	ds_read_b128 v[176:179], v80 offset:49152
	s_waitcnt lgkmcnt(3)
	v_pk_mul_f32 v[28:29], v[28:29], v[162:163]
	s_waitcnt lgkmcnt(2)
	v_pk_mul_f32 v[24:25], v[24:25], v[166:167]
	s_waitcnt lgkmcnt(1)
	v_pk_mul_f32 v[20:21], v[20:21], v[172:173]
	v_pk_mul_f32 v[30:31], v[30:31], v[164:165]
	v_pk_mul_f32 v[26:27], v[26:27], v[168:169]
	v_pk_mul_f32 v[22:23], v[22:23], v[174:175]
	s_waitcnt lgkmcnt(0)
	v_pk_mul_f32 v[18:19], v[18:19], v[178:179]
	v_pk_mul_f32 v[16:17], v[16:17], v[176:177]
	v_pk_mul_f32 v[12:13], v[12:13], v[162:163]
	v_pk_mul_f32 v[8:9], v[8:9], v[166:167]
	v_pk_mul_f32 v[4:5], v[4:5], v[172:173]
	v_pk_mul_f32 v[14:15], v[14:15], v[164:165]
	v_pk_mul_f32 v[10:11], v[10:11], v[168:169]
	v_pk_mul_f32 v[6:7], v[6:7], v[174:175]
	v_pk_mul_f32 v[2:3], v[2:3], v[178:179]
	v_pk_mul_f32 v[0:1], v[0:1], v[176:177]
.LBB0_335:
	s_add_i32 s20, s45, 0x2000
	s_cmpk_lg_i32 s45, 0x4000
	s_cselect_b32 s43, s20, 0
	v_add_u32_e32 v80, s48, v214
	ds_read_b64_tr_b16 v[166:167], v80 offset:24576
	ds_read_b64_tr_b16 v[168:169], v80 offset:25088
	v_pk_add_f32 v[188:189], v[60:61], v[62:63]
	s_setprio 1
	s_waitcnt lgkmcnt(4)
	v_mfma_f32_32x32x16_bf16 v[98:113], v[158:161], v[126:129], v[98:113]
	s_setprio 0
	v_pk_add_f32 v[188:189], v[188:189], v[64:65]
	v_pk_add_f32 v[188:189], v[188:189], v[66:67]
	v_cvt_pk_bf16_f32 v142, v60, v61
	v_cvt_pk_bf16_f32 v143, v62, v63
	ds_read_b64_tr_b16 v[158:159], v80 offset:28672
	ds_read_b64_tr_b16 v[160:161], v80 offset:29184
	s_setprio 1
	s_waitcnt lgkmcnt(4)
	v_mfma_f32_32x32x16_bf16 v[82:97], v[150:153], v[126:129], v[82:97]
	s_setprio 0
	v_pk_add_f32 v[188:189], v[188:189], v[68:69]
	v_pk_add_f32 v[188:189], v[188:189], v[70:71]
	v_cvt_pk_bf16_f32 v144, v64, v65
	v_cvt_pk_bf16_f32 v145, v66, v67
	ds_read_b64_tr_b16 v[150:151], v80 offset:25600
	ds_read_b64_tr_b16 v[152:153], v80 offset:26112
	s_setprio 1
	v_mfma_f32_32x32x16_bf16 v[98:113], v[154:157], v[122:125], v[98:113]
	s_setprio 0
	v_pk_add_f32 v[188:189], v[188:189], v[72:73]
	v_pk_add_f32 v[188:189], v[188:189], v[74:75]
	v_cvt_pk_bf16_f32 v138, v68, v69
	v_cvt_pk_bf16_f32 v139, v70, v71
	ds_read_b64_tr_b16 v[162:163], v80 offset:29696
	ds_read_b64_tr_b16 v[164:165], v80 offset:30208
	s_setprio 1
	v_mfma_f32_32x32x16_bf16 v[82:97], v[76:79], v[122:125], v[82:97]
	s_setprio 0
	v_pk_add_f32 v[188:189], v[188:189], v[32:33]
	v_pk_add_f32 v[188:189], v[188:189], v[34:35]
	v_cvt_pk_bf16_f32 v140, v72, v73
	v_cvt_pk_bf16_f32 v141, v74, v75
	ds_read_b64_tr_b16 v[64:65], v80 offset:26624
	ds_read_b64_tr_b16 v[66:67], v80 offset:27136
	s_setprio 1
	v_mfma_f32_32x32x16_bf16 v[98:113], v[146:149], v[118:121], v[98:113]
	s_setprio 0
	v_pk_add_f32 v[188:189], v[188:189], v[36:37]
	v_pk_add_f32 v[188:189], v[188:189], v[38:39]
	v_cvt_pk_bf16_f32 v134, v32, v33
	v_cvt_pk_bf16_f32 v135, v34, v35
	ds_read_b64_tr_b16 v[60:61], v80 offset:30720
	ds_read_b64_tr_b16 v[62:63], v80 offset:31232
	s_setprio 1
	v_mfma_f32_32x32x16_bf16 v[82:97], v[52:55], v[118:121], v[82:97]
	s_setprio 0
	v_pk_add_f32 v[188:189], v[188:189], v[40:41]
	v_pk_add_f32 v[188:189], v[188:189], v[42:43]
	v_cvt_pk_bf16_f32 v136, v36, v37
	v_cvt_pk_bf16_f32 v137, v38, v39
	ds_read_b64_tr_b16 v[36:37], v80 offset:27648
	ds_read_b64_tr_b16 v[38:39], v80 offset:28160
	s_setprio 1
	v_mfma_f32_32x32x16_bf16 v[98:113], v[56:59], v[114:117], v[98:113]
	s_setprio 0
	v_pk_add_f32 v[188:189], v[188:189], v[44:45]
	v_pk_add_f32 v[188:189], v[188:189], v[46:47]
	v_cvt_pk_bf16_f32 v130, v40, v41
	v_cvt_pk_bf16_f32 v131, v42, v43
	ds_read_b64_tr_b16 v[32:33], v80 offset:31744
	ds_read_b64_tr_b16 v[34:35], v80 offset:32256
	s_setprio 1
	v_mfma_f32_32x32x16_bf16 v[82:97], v[48:51], v[114:117], v[82:97]
	s_setprio 0
	v_add_f32_e32 v40, v188, v189
	v_cvt_pk_bf16_f32 v132, v44, v45
	v_cvt_pk_bf16_f32 v133, v46, v47
	v_max_f32_e32 v41, v99, v99
	v_max_f32_e32 v42, v98, v98
	v_max_f32_e32 v41, v42, v41
	s_nop 2
	v_max3_f32 v42, v100, v101, v83
	v_max3_f32 v41, v41, v82, v84
	v_max3_f32 v41, v41, v85, v102
	v_max3_f32 v42, v42, v104, v105
	v_max3_f32 v41, v41, v103, v86
	v_max3_f32 v42, v42, v88, v89
	v_max3_f32 v41, v41, v87, v106
	v_max3_f32 v42, v42, v108, v109
	v_max3_f32 v41, v41, v107, v90
	v_max3_f32 v42, v42, v92, v93
	v_max3_f32 v41, v41, v91, v110
	v_max3_f32 v42, v42, v112, v113
	v_max3_f32 v41, v41, v111, v94
	v_max3_f32 v42, v42, v96, v97
	v_add_f32_e32 v203, v170, v40
	v_max3_f32 v40, v41, v95, v42
	v_mov_b32_e32 v41, v40
	s_nop 1
	v_permlane32_swap_b32_e32 v40, v41
	v_max_f32_e32 v41, v41, v41
	v_max_f32_e32 v40, v40, v40
	v_max_f32_e32 v40, v40, v41
	s_add_i32 s20, s45, s40
	s_mov_b32 s21, m0
	s_mov_b32 m0, s20
	s_nop 0
	global_load_lds_dwordx4 v211, s[18:19]
	s_mov_b32 m0, s21
	v_sub_f32_e32 v40, v40, v206
	s_add_i32 s20, s43, s41
	s_mov_b32 s21, m0
	s_mov_b32 m0, s20
	s_nop 0
	global_load_lds_dwordx4 v212, s[0:1]
	s_mov_b32 m0, s21
	v_cmp_lt_f32_e32 vcc, s35, v40
	s_cmp_lg_u64 vcc, 0
	s_cselect_b64 s[20:21], -1, 0
	s_cbranch_vccz .LBB0_339
	v_max_f32_e32 v40, v40, v40
	v_max_f32_e32 v41, 0, v40
	v_exp_f32_e64 v40, -v41
	s_and_saveexec_b64 s[22:23], s[4:5]
	ds_write_b32 v199, v40 offset:49152
	s_or_b64 exec, exec, s[22:23]
	v_add_f32_e32 v206, v206, v41
	v_mul_f32_e32 v203, v203, v40
